# LDS bank conflicts: K tile 16-byte chunk pairs swapped on rows 4..11 of each 16-key subtile so every ds_read_b128 lane group of a K fragment read hits 16 distinct slots (writer and all QK readers agre
# speedup vs baseline: 1.0055x; 1.0003x over previous
; #define LAS __attribute__((address_space(3)))
; template <bool DOK, bool DOV>
; __device__ __forceinline__ void stage_load(StageRegs& R, const bf16_t* Kg, const bf16_t* VTg, int vpitch, int key0, int tid) {
; #pragma unroll
;     for (int i = 0; i < 2; ++i) {
;         const int idx = tid + i * 512;
;         if (DOK) R.k[i] = *(const u32x4*)(Kg + (size_t)(key0 + (idx >> 4)) * 128 + (idx & 15) * 8);
;         if (DOV) R.v[i] = *(const u32x4*)(VTg + (size_t)(idx >> 3) * vpitch + key0 + (idx & 7) * 8);
;     }
; }
; template <bool DOK, bool DOV>
; __device__ __forceinline__ void stage_store(const StageRegs& R, LAS unsigned char* buf, int tid) {
; #pragma unroll
;     for (int i = 0; i < 2; ++i) {
;         const int idx = tid + i * 512;
;         if (DOK) *(LAS u32x4*)(buf + (idx >> 4) * KT_PITCH + (idx & 15) * 16) = R.k[i];
;         if (DOV) *(LAS u32x4*)(buf + KB_BYTES + (idx >> 3) * VT_PITCH + (idx & 7) * 16) = R.v[i];
;     }
; }
; template <int MODE> ...
;     float mrun[2] = {NEG_BIG, NEG_BIG}; lsum[0] = 0.f; lsum[1] = 0.f;
; #pragma unroll
;     for (int gp = 0; gp < 2; ++gp)
; #pragma unroll
;         for (int dt = 0; dt < 8; ++dt) o[gp][dt] = (f32x4){0.f, 0.f, 0.f, 0.f};
;     StageRegs R; stage_load<true, true>(R, Kg, VTg, vpitch, tile_lo * 64, tid);
;     __syncthreads();
;     stage_store<true, true>(R, lds + (tile_lo & 1) * BUF_BYTES, tid);
;     __syncthreads();
;     int tile = tile_lo;
.LBB0_959:
	s_lshl_b64 s[10:11], s[36:37], 16
	s_add_u32 s12, s73, s10
	s_addc_u32 s13, s86, s11
	v_lshlrev_b32_e32 v2, 3, v225
	s_add_u32 s10, s87, s10
	v_and_b32_e32 v0, 0x78, v2
	v_and_b32_e32 v2, 56, v2
	s_addc_u32 s11, s88, s11
	v_lshlrev_b32_e32 v2, 1, v2
	v_mov_b32_e32 v3, v1
	v_lshl_add_u64 v[174:175], s[10:11], 0, v[2:3]
	v_ashrrev_i32_e32 v166, 3, v225
	v_add_u32_e32 v3, 0x200, v225
	v_ashrrev_i32_e32 v150, 4, v225
	v_ashrrev_i32_e32 v167, 31, v166
	v_ashrrev_i32_e32 v170, 3, v3
	v_lshlrev_b32_e32 v0, 1, v0
	v_ashrrev_i32_e32 v151, 31, v150
	v_lshlrev_b64 v[182:183], 9, v[166:167]
	v_ashrrev_i32_e32 v152, 4, v3
	v_ashrrev_i32_e32 v171, 31, v170
	v_lshl_add_u64 v[176:177], s[12:13], 0, v[0:1]
	v_lshlrev_b64 v[164:165], 8, v[150:151]
	v_lshl_add_u64 v[36:37], v[174:175], 0, v[182:183]
	v_ashrrev_i32_e32 v153, 31, v152
	v_lshlrev_b64 v[184:185], 9, v[170:171]
	v_lshl_add_u64 v[178:179], v[176:177], 0, v[164:165]
	global_load_dwordx4 v[100:103], v[36:37], off
	v_lshlrev_b64 v[168:169], 8, v[152:153]
	v_lshl_add_u64 v[36:37], v[174:175], 0, v[184:185]
	v_lshl_add_u64 v[180:181], v[176:177], 0, v[168:169]
	global_load_dwordx4 v[104:107], v[178:179], off
	global_load_dwordx4 v[108:111], v[180:181], off
	global_load_dwordx4 v[112:115], v[36:37], off
	v_lshlrev_b32_e32 v3, 4, v225
	v_subrev_u32_e32 v36, 31, v216
	v_and_b32_e32 v205, 0xf0, v3
	v_and_b32_e32 v206, 0x70, v3
	v_lshl_add_u32 v3, v150, 1, 8
	v_and_b32_e32 v3, 16, v3
	v_xor_b32_e32 v205, v205, v3
	v_subrev_u32_e32 v37, 31, v215
	v_mul_lo_u32 v207, v150, s5
	v_mul_lo_u32 v208, v166, s35
	v_ashrrev_i32_e32 v236, 4, v36
	v_add_u32_e32 v221, 0, v205
	v_add_u32_e32 v36, 0, v206
	v_mul_lo_u32 v209, v152, s5
	v_mul_lo_u32 v210, v170, s35
	s_ashr_i32 s16, s0, 4
	s_mov_b64 s[10:11], -1
	v_lshlrev_b32_e32 v149, 4, v220
	v_lshl_add_u32 v3, v211, 1, 8
	v_and_b32_e32 v3, 16, v3
	v_xor_b32_e32 v149, v149, v3
	v_mul_lo_u32 v201, v211, s5
	v_mul_lo_u32 v204, v211, s35
	v_lshlrev_b32_e32 v217, 2, v220
	v_add_u32_e32 v3, 64, v150
	v_add_u32_e32 v222, 64, v152
	v_add_u32_e32 v195, v221, v207
	v_add_u32_e32 v212, v36, v208
	v_add_u32_e32 v213, v221, v209
	v_add_u32_e32 v214, v36, v210
	s_cmp_gt_i32 s16, -1
	v_ashrrev_i32_e32 v237, 4, v37
	s_waitcnt vmcnt(0) lgkmcnt(0)
	s_barrier
	ds_write_b128 v195, v[104:107]
	ds_write_b128 v212, v[100:103] offset:17408
	ds_write_b128 v213, v[108:111]
	ds_write_b128 v214, v[112:115] offset:17408
	s_waitcnt lgkmcnt(0)
	s_barrier
	s_cbranch_scc0 .LBB0_968
	v_lshlrev_b32_e32 v156, 2, v220
	v_mov_b32_e32 v36, 0
	s_add_i32 s18, s16, 1
	v_sub_u32_e32 v157, v237, v156
	v_sub_u32_e32 v159, v236, v156
	v_mov_b32_e32 v163, 0xf149f2ca
	s_mov_b32 s10, 0
	s_mov_b32 s19, 0
	v_mov_b32_e32 v37, v36
	v_mov_b32_e32 v38, v36
	v_mov_b32_e32 v39, v36
	v_mov_b32_e32 v40, v36
	v_mov_b32_e32 v41, v36
	v_mov_b32_e32 v42, v36
	v_mov_b32_e32 v43, v36
	v_mov_b32_e32 v44, v36
	v_mov_b32_e32 v45, v36
	v_mov_b32_e32 v46, v36
	v_mov_b32_e32 v47, v36
	v_mov_b32_e32 v48, v36
	v_mov_b32_e32 v49, v36
	v_mov_b32_e32 v50, v36
	v_mov_b32_e32 v51, v36
	v_mov_b32_e32 v52, v36
	v_mov_b32_e32 v53, v36
	v_mov_b32_e32 v54, v36
	v_mov_b32_e32 v55, v36
	v_mov_b32_e32 v56, v36
	v_mov_b32_e32 v57, v36
	v_mov_b32_e32 v58, v36
	v_mov_b32_e32 v59, v36
	v_mov_b32_e32 v60, v36
	v_mov_b32_e32 v61, v36
	v_mov_b32_e32 v62, v36
	v_mov_b32_e32 v63, v36
	v_mov_b32_e32 v64, v36
	v_mov_b32_e32 v65, v36
	v_mov_b32_e32 v66, v36
	v_mov_b32_e32 v67, v36
	v_mov_b32_e32 v68, v36
	v_mov_b32_e32 v69, v36
	v_mov_b32_e32 v70, v36
	v_mov_b32_e32 v71, v36
	v_mov_b32_e32 v72, v36
	v_mov_b32_e32 v73, v36
	v_mov_b32_e32 v74, v36
	v_mov_b32_e32 v75, v36
	v_mov_b32_e32 v76, v36
	v_mov_b32_e32 v77, v36
	v_mov_b32_e32 v78, v36
	v_mov_b32_e32 v79, v36
	v_mov_b32_e32 v80, v36
	v_mov_b32_e32 v81, v36
	v_mov_b32_e32 v82, v36
	v_mov_b32_e32 v83, v36
	v_mov_b32_e32 v84, v36
	v_mov_b32_e32 v85, v36
	v_mov_b32_e32 v86, v36
	v_mov_b32_e32 v87, v36
	v_mov_b32_e32 v88, v36
	v_mov_b32_e32 v89, v36
	v_mov_b32_e32 v90, v36
	v_mov_b32_e32 v91, v36
	v_mov_b32_e32 v92, v36
	v_mov_b32_e32 v93, v36
	v_mov_b32_e32 v94, v36
	v_mov_b32_e32 v95, v36
	v_mov_b32_e32 v96, v36
	v_mov_b32_e32 v97, v36
	v_mov_b32_e32 v98, v36
	v_mov_b32_e32 v99, v36
	v_mov_b32_e32 v202, 0xf149f2ca
	v_mov_b32_e32 v172, v36
	v_mov_b32_e32 v173, v36
